# c1 plus hand-written MLP-up epilogue (one SGPR base, 8 lane-offset VGPRs, no canonicalise, 303 vs 578 instructions)
# speedup vs baseline: 1.0059x; 1.0059x over previous
; __device__ __forceinline__ unsigned pk2(float lo, float hi) { f32x2 v = {lo, hi}; bf16x2_t b = __builtin_convertvector(v, bf16x2_t); return __builtin_bit_cast(unsigned, b); }
; __host__ __device__ __forceinline__ size_t blk_off(int row, int k, int K, bool perm) {
;     const int r = row & 127, slot = perm ? ((r & ~31) + perm32inv(r & 31)) : r; return ((size_t)(row >> 7) * (K >> 6) + (k >> 6)) * BLK + lds_byte(slot, k & 63); }
;     __device__ __forceinline__ void operator()(const AccT& acc, const Unit& u, int wr, int wc, int fr_in, int fq_in) const {
;         int fr = fr_in, fq = fq_in; asm volatile("" : "+v"(fr), "+v"(fq));
;         const int row0 = u.pm * BM + wr * 64 + fr, col0 = u.pn * BM + wc * 32 + 8 * fq;
; #pragma unroll
;         for (int ai = 0; ai < 2; ++ai)
; #pragma unroll
;             for (int m = 0; m < 4; ++m) { const int row = row0 + ai * HALF + m * 16;
; #pragma unroll
;                 for (int bj = 0; bj < 2; ++bj) { f32x4 v0 = acc[ai][bj][m][0], v1 = acc[ai][bj][m][1];
; #pragma unroll
;                     for (int j = 0; j < 4; ++j) { const float a = fmaxf(v0[j], 0.f), b = fmaxf(v1[j], 0.f); v0[j] = a * a; v1[j] = b * b; }
;                     u32x4 w; w.x = pk2(v0[0], v0[1]); w.y = pk2(v0[2], v0[3]); w.z = pk2(v1[0], v1[1]); w.w = pk2(v1[2], v1[3]);
;                     *(u32x4*)((char*)O + blk_off(row, col0 + bj * HALF, Kd, false)) = w; } }
;     }
.LBB0_1157:
	s_lshl_b32 s0, s37, 22
	s_lshl_b32 s1, s36, 16
	s_add_i32 s0, s0, s1
	s_and_b32 s1, s49, 64
	s_lshl_b32 s1, s1, 8
	s_add_i32 s0, s0, s1
	s_lshl_b32 s1, s48, 7
	s_add_i32 s0, s0, s1
	s_and_b32 s1, s49, 32
	s_lshl_b32 s1, s1, 5
	s_add_i32 s0, s0, s1
	s_add_u32 s0, s52, s0
	s_addc_u32 s1, s53, 0
	v_lshlrev_b32_e32 v139, 6, v1
	v_lshl_add_u32 v139, v136, 4, v139
	v_and_b32_e32 v140, 8, v1
	v_lshlrev_b32_e32 v140, 2, v140
	v_xor_b32_e32 v139, v139, v140
	v_add_u32_e32 v140, 0x8000, v139
	v_add_u32_e32 v141, 0x1000, v139
	v_add_u32_e32 v142, 0x9000, v139
	v_add_u32_e32 v143, 0x200000, v139
	v_add_u32_e32 v144, 0x208000, v139
	v_add_u32_e32 v145, 0x201000, v139
	v_add_u32_e32 v146, 0x209000, v139
	v_max_f32_e32 v126, 0, v126
	v_max_f32_e32 v127, 0, v127
	v_max_f32_e32 v128, 0, v128
	v_max_f32_e32 v129, 0, v129
	v_max_f32_e32 v122, 0, v122
	v_max_f32_e32 v123, 0, v123
	v_max_f32_e32 v124, 0, v124
	v_max_f32_e32 v125, 0, v125
	v_pk_mul_f32 v[126:127], v[126:127], v[126:127]
	v_pk_mul_f32 v[128:129], v[128:129], v[128:129]
	v_pk_mul_f32 v[122:123], v[122:123], v[122:123]
	v_pk_mul_f32 v[124:125], v[124:125], v[124:125]
	v_cvt_pk_bf16_f32 v126, v126, v127
	v_cvt_pk_bf16_f32 v127, v128, v129
	v_cvt_pk_bf16_f32 v128, v122, v123
	v_cvt_pk_bf16_f32 v129, v124, v125
	global_store_dwordx4 v139, v[126:129], s[0:1]
	v_max_f32_e32 v118, 0, v118
	v_max_f32_e32 v119, 0, v119
	v_max_f32_e32 v120, 0, v120
	v_max_f32_e32 v121, 0, v121
	v_max_f32_e32 v114, 0, v114
	v_max_f32_e32 v115, 0, v115
	v_max_f32_e32 v116, 0, v116
	v_max_f32_e32 v117, 0, v117
	v_pk_mul_f32 v[118:119], v[118:119], v[118:119]
	v_pk_mul_f32 v[120:121], v[120:121], v[120:121]
	v_pk_mul_f32 v[114:115], v[114:115], v[114:115]
	v_pk_mul_f32 v[116:117], v[116:117], v[116:117]
	v_cvt_pk_bf16_f32 v118, v118, v119
	v_cvt_pk_bf16_f32 v119, v120, v121
	v_cvt_pk_bf16_f32 v120, v114, v115
	v_cvt_pk_bf16_f32 v121, v116, v117
	global_store_dwordx4 v140, v[118:121], s[0:1]
	v_max_f32_e32 v110, 0, v110
	v_max_f32_e32 v111, 0, v111
	v_max_f32_e32 v112, 0, v112
	v_max_f32_e32 v113, 0, v113
	v_max_f32_e32 v106, 0, v106
	v_max_f32_e32 v107, 0, v107
	v_max_f32_e32 v108, 0, v108
	v_max_f32_e32 v109, 0, v109
	v_pk_mul_f32 v[110:111], v[110:111], v[110:111]
	v_pk_mul_f32 v[112:113], v[112:113], v[112:113]
	v_pk_mul_f32 v[106:107], v[106:107], v[106:107]
	v_pk_mul_f32 v[108:109], v[108:109], v[108:109]
	v_cvt_pk_bf16_f32 v110, v110, v111
	v_cvt_pk_bf16_f32 v111, v112, v113
	v_cvt_pk_bf16_f32 v112, v106, v107
	v_cvt_pk_bf16_f32 v113, v108, v109
	global_store_dwordx4 v139, v[110:113], s[0:1] offset:2048
	v_max_f32_e32 v102, 0, v102
	v_max_f32_e32 v103, 0, v103
	v_max_f32_e32 v104, 0, v104
	v_max_f32_e32 v105, 0, v105
	v_max_f32_e32 v98, 0, v98
	v_max_f32_e32 v99, 0, v99
	v_max_f32_e32 v100, 0, v100
	v_max_f32_e32 v101, 0, v101
	v_pk_mul_f32 v[102:103], v[102:103], v[102:103]
	v_pk_mul_f32 v[104:105], v[104:105], v[104:105]
	v_pk_mul_f32 v[98:99], v[98:99], v[98:99]
	v_pk_mul_f32 v[100:101], v[100:101], v[100:101]
	v_cvt_pk_bf16_f32 v102, v102, v103
	v_cvt_pk_bf16_f32 v103, v104, v105
	v_cvt_pk_bf16_f32 v104, v98, v99
	v_cvt_pk_bf16_f32 v105, v100, v101
	global_store_dwordx4 v140, v[102:105], s[0:1] offset:2048
	v_max_f32_e32 v94, 0, v94
	v_max_f32_e32 v95, 0, v95
	v_max_f32_e32 v96, 0, v96
	v_max_f32_e32 v97, 0, v97
	v_max_f32_e32 v90, 0, v90
	v_max_f32_e32 v91, 0, v91
	v_max_f32_e32 v92, 0, v92
	v_max_f32_e32 v93, 0, v93
	v_pk_mul_f32 v[94:95], v[94:95], v[94:95]
	v_pk_mul_f32 v[96:97], v[96:97], v[96:97]
	v_pk_mul_f32 v[90:91], v[90:91], v[90:91]
	v_pk_mul_f32 v[92:93], v[92:93], v[92:93]
	v_cvt_pk_bf16_f32 v94, v94, v95
	v_cvt_pk_bf16_f32 v95, v96, v97
	v_cvt_pk_bf16_f32 v96, v90, v91
	v_cvt_pk_bf16_f32 v97, v92, v93
	global_store_dwordx4 v141, v[94:97], s[0:1]
	v_max_f32_e32 v86, 0, v86
	v_max_f32_e32 v87, 0, v87
	v_max_f32_e32 v88, 0, v88
	v_max_f32_e32 v89, 0, v89
	v_max_f32_e32 v82, 0, v82
	v_max_f32_e32 v83, 0, v83
	v_max_f32_e32 v84, 0, v84
	v_max_f32_e32 v85, 0, v85
	v_pk_mul_f32 v[86:87], v[86:87], v[86:87]
	v_pk_mul_f32 v[88:89], v[88:89], v[88:89]
	v_pk_mul_f32 v[82:83], v[82:83], v[82:83]
	v_pk_mul_f32 v[84:85], v[84:85], v[84:85]
	v_cvt_pk_bf16_f32 v86, v86, v87
	v_cvt_pk_bf16_f32 v87, v88, v89
	v_cvt_pk_bf16_f32 v88, v82, v83
	v_cvt_pk_bf16_f32 v89, v84, v85
	global_store_dwordx4 v142, v[86:89], s[0:1]
	v_max_f32_e32 v78, 0, v78
	v_max_f32_e32 v79, 0, v79
	v_max_f32_e32 v80, 0, v80
	v_max_f32_e32 v81, 0, v81
	v_max_f32_e32 v74, 0, v74
	v_max_f32_e32 v75, 0, v75
	v_max_f32_e32 v76, 0, v76
	v_max_f32_e32 v77, 0, v77
	v_pk_mul_f32 v[78:79], v[78:79], v[78:79]
	v_pk_mul_f32 v[80:81], v[80:81], v[80:81]
	v_pk_mul_f32 v[74:75], v[74:75], v[74:75]
	v_pk_mul_f32 v[76:77], v[76:77], v[76:77]
	v_cvt_pk_bf16_f32 v78, v78, v79
	v_cvt_pk_bf16_f32 v79, v80, v81
	v_cvt_pk_bf16_f32 v80, v74, v75
	v_cvt_pk_bf16_f32 v81, v76, v77
	global_store_dwordx4 v141, v[78:81], s[0:1] offset:2048
	v_max_f32_e32 v70, 0, v70
	v_max_f32_e32 v71, 0, v71
	v_max_f32_e32 v72, 0, v72
	v_max_f32_e32 v73, 0, v73
	v_max_f32_e32 v66, 0, v66
	v_max_f32_e32 v67, 0, v67
	v_max_f32_e32 v68, 0, v68
	v_max_f32_e32 v69, 0, v69
; __device__ __forceinline__ unsigned pk2(float lo, float hi) { f32x2 v = {lo, hi}; bf16x2_t b = __builtin_convertvector(v, bf16x2_t); return __builtin_bit_cast(unsigned, b); }
; #define PG8_BAR __builtin_amdgcn_s_barrier()
; template <class Epi, bool ALIGN_EPI = true, bool SP2 = true>
; __device__ __forceinline__ void gemm_phase(LAS unsigned char* lds, const Gemm g, const StaticOrder& S, const Epi& E, unsigned long long& tacc, const int tmode) {
;     ...
;         if (!has_next) { if (tmode == 2) tacc += __builtin_amdgcn_s_memrealtime() - tk0; break; }
; #pragma unroll
;         for (int a = 0; a < 2; ++a)
; #pragma unroll
;             for (int b = 0; b < 2; ++b)
; #pragma unroll
;                 for (int m = 0; m < 4; ++m)
; #pragma unroll
;                     for (int n = 0; n < 2; ++n) acc[a][b][m][n] = (f32x4){0.f, 0.f, 0.f, 0.f};
;         cur = nxt; cA = nA; cB = nB; ++ui;
;         if constexpr (ALIGN_EPI) { if (wr == 1) PG8_BAR; }
;     __device__ __forceinline__ void operator()(const AccT& acc, const Unit& u, int wr, int wc, int fr_in, int fq_in) const {
;     ...
;             for (int m = 0; m < 4; ++m) { const int row = row0 + ai * HALF + m * 16;
; #pragma unroll
;                 for (int bj = 0; bj < 2; ++bj) { f32x4 v0 = acc[ai][bj][m][0], v1 = acc[ai][bj][m][1];
; #pragma unroll
;                     for (int j = 0; j < 4; ++j) { const float a = fmaxf(v0[j], 0.f), b = fmaxf(v1[j], 0.f); v0[j] = a * a; v1[j] = b * b; }
;                     u32x4 w; w.x = pk2(v0[0], v0[1]); w.y = pk2(v0[2], v0[3]); w.z = pk2(v1[0], v1[1]); w.w = pk2(v1[2], v1[3]);
;                     *(u32x4*)((char*)O + blk_off(row, col0 + bj * HALF, Kd, false)) = w; } }
	v_pk_mul_f32 v[70:71], v[70:71], v[70:71]
	v_pk_mul_f32 v[72:73], v[72:73], v[72:73]
	v_pk_mul_f32 v[66:67], v[66:67], v[66:67]
	v_pk_mul_f32 v[68:69], v[68:69], v[68:69]
	v_cvt_pk_bf16_f32 v70, v70, v71
	v_cvt_pk_bf16_f32 v71, v72, v73
	v_cvt_pk_bf16_f32 v72, v66, v67
	v_cvt_pk_bf16_f32 v73, v68, v69
	global_store_dwordx4 v142, v[70:73], s[0:1] offset:2048
	v_max_f32_e32 v62, 0, v62
	v_max_f32_e32 v63, 0, v63
	v_max_f32_e32 v64, 0, v64
	v_max_f32_e32 v65, 0, v65
	v_max_f32_e32 v58, 0, v58
	v_max_f32_e32 v59, 0, v59
	v_max_f32_e32 v60, 0, v60
	v_max_f32_e32 v61, 0, v61
	v_pk_mul_f32 v[62:63], v[62:63], v[62:63]
	v_pk_mul_f32 v[64:65], v[64:65], v[64:65]
	v_pk_mul_f32 v[58:59], v[58:59], v[58:59]
	v_pk_mul_f32 v[60:61], v[60:61], v[60:61]
	v_cvt_pk_bf16_f32 v62, v62, v63
	v_cvt_pk_bf16_f32 v63, v64, v65
	v_cvt_pk_bf16_f32 v64, v58, v59
	v_cvt_pk_bf16_f32 v65, v60, v61
	global_store_dwordx4 v143, v[62:65], s[0:1]
	v_max_f32_e32 v54, 0, v54
	v_max_f32_e32 v55, 0, v55
	v_max_f32_e32 v56, 0, v56
	v_max_f32_e32 v57, 0, v57
	v_max_f32_e32 v50, 0, v50
	v_max_f32_e32 v51, 0, v51
	v_max_f32_e32 v52, 0, v52
	v_max_f32_e32 v53, 0, v53
	v_pk_mul_f32 v[54:55], v[54:55], v[54:55]
	v_pk_mul_f32 v[56:57], v[56:57], v[56:57]
	v_pk_mul_f32 v[50:51], v[50:51], v[50:51]
	v_pk_mul_f32 v[52:53], v[52:53], v[52:53]
	v_cvt_pk_bf16_f32 v54, v54, v55
	v_cvt_pk_bf16_f32 v55, v56, v57
	v_cvt_pk_bf16_f32 v56, v50, v51
	v_cvt_pk_bf16_f32 v57, v52, v53
	global_store_dwordx4 v144, v[54:57], s[0:1]
	v_max_f32_e32 v46, 0, v46
	v_max_f32_e32 v47, 0, v47
	v_max_f32_e32 v48, 0, v48
	v_max_f32_e32 v49, 0, v49
	v_max_f32_e32 v42, 0, v42
	v_max_f32_e32 v43, 0, v43
	v_max_f32_e32 v44, 0, v44
	v_max_f32_e32 v45, 0, v45
	v_pk_mul_f32 v[46:47], v[46:47], v[46:47]
	v_pk_mul_f32 v[48:49], v[48:49], v[48:49]
	v_pk_mul_f32 v[42:43], v[42:43], v[42:43]
	v_pk_mul_f32 v[44:45], v[44:45], v[44:45]
	v_cvt_pk_bf16_f32 v46, v46, v47
	v_cvt_pk_bf16_f32 v47, v48, v49
	v_cvt_pk_bf16_f32 v48, v42, v43
	v_cvt_pk_bf16_f32 v49, v44, v45
	global_store_dwordx4 v143, v[46:49], s[0:1] offset:2048
	v_max_f32_e32 v38, 0, v38
	v_max_f32_e32 v39, 0, v39
	v_max_f32_e32 v40, 0, v40
	v_max_f32_e32 v41, 0, v41
	v_max_f32_e32 v34, 0, v34
	v_max_f32_e32 v35, 0, v35
	v_max_f32_e32 v36, 0, v36
	v_max_f32_e32 v37, 0, v37
	v_pk_mul_f32 v[38:39], v[38:39], v[38:39]
	v_pk_mul_f32 v[40:41], v[40:41], v[40:41]
	v_pk_mul_f32 v[34:35], v[34:35], v[34:35]
	v_pk_mul_f32 v[36:37], v[36:37], v[36:37]
	v_cvt_pk_bf16_f32 v38, v38, v39
	v_cvt_pk_bf16_f32 v39, v40, v41
	v_cvt_pk_bf16_f32 v40, v34, v35
	v_cvt_pk_bf16_f32 v41, v36, v37
	global_store_dwordx4 v144, v[38:41], s[0:1] offset:2048
	v_max_f32_e32 v30, 0, v30
	v_max_f32_e32 v31, 0, v31
	v_max_f32_e32 v32, 0, v32
	v_max_f32_e32 v33, 0, v33
	v_max_f32_e32 v26, 0, v26
	v_max_f32_e32 v27, 0, v27
	v_max_f32_e32 v28, 0, v28
	v_max_f32_e32 v29, 0, v29
	v_pk_mul_f32 v[30:31], v[30:31], v[30:31]
	v_pk_mul_f32 v[32:33], v[32:33], v[32:33]
	v_pk_mul_f32 v[26:27], v[26:27], v[26:27]
	v_pk_mul_f32 v[28:29], v[28:29], v[28:29]
	v_cvt_pk_bf16_f32 v30, v30, v31
	v_cvt_pk_bf16_f32 v31, v32, v33
	v_cvt_pk_bf16_f32 v32, v26, v27
	v_cvt_pk_bf16_f32 v33, v28, v29
	global_store_dwordx4 v145, v[30:33], s[0:1]
	v_max_f32_e32 v22, 0, v22
	v_max_f32_e32 v23, 0, v23
	v_max_f32_e32 v24, 0, v24
	v_max_f32_e32 v25, 0, v25
	v_max_f32_e32 v18, 0, v18
	v_max_f32_e32 v19, 0, v19
	v_max_f32_e32 v20, 0, v20
	v_max_f32_e32 v21, 0, v21
	v_pk_mul_f32 v[22:23], v[22:23], v[22:23]
	v_pk_mul_f32 v[24:25], v[24:25], v[24:25]
	v_pk_mul_f32 v[18:19], v[18:19], v[18:19]
	v_pk_mul_f32 v[20:21], v[20:21], v[20:21]
	v_cvt_pk_bf16_f32 v22, v22, v23
	v_cvt_pk_bf16_f32 v23, v24, v25
	v_cvt_pk_bf16_f32 v24, v18, v19
	v_cvt_pk_bf16_f32 v25, v20, v21
	global_store_dwordx4 v146, v[22:25], s[0:1]
	v_max_f32_e32 v14, 0, v14
	v_max_f32_e32 v15, 0, v15
	v_max_f32_e32 v16, 0, v16
	v_max_f32_e32 v17, 0, v17
	v_max_f32_e32 v10, 0, v10
	v_max_f32_e32 v11, 0, v11
	v_max_f32_e32 v12, 0, v12
	v_max_f32_e32 v13, 0, v13
	v_pk_mul_f32 v[14:15], v[14:15], v[14:15]
	v_pk_mul_f32 v[16:17], v[16:17], v[16:17]
	v_pk_mul_f32 v[10:11], v[10:11], v[10:11]
	v_pk_mul_f32 v[12:13], v[12:13], v[12:13]
	v_cvt_pk_bf16_f32 v14, v14, v15
	v_cvt_pk_bf16_f32 v15, v16, v17
	v_cvt_pk_bf16_f32 v16, v10, v11
	v_cvt_pk_bf16_f32 v17, v12, v13
	global_store_dwordx4 v145, v[14:17], s[0:1] offset:2048
	v_max_f32_e32 v6, 0, v6
	v_max_f32_e32 v7, 0, v7
	v_max_f32_e32 v8, 0, v8
	v_max_f32_e32 v9, 0, v9
	v_max_f32_e32 v2, 0, v2
	v_max_f32_e32 v3, 0, v3
	v_max_f32_e32 v4, 0, v4
	v_max_f32_e32 v5, 0, v5
	v_pk_mul_f32 v[6:7], v[6:7], v[6:7]
	v_pk_mul_f32 v[8:9], v[8:9], v[8:9]
	v_pk_mul_f32 v[2:3], v[2:3], v[2:3]
	v_pk_mul_f32 v[4:5], v[4:5], v[4:5]
	v_cvt_pk_bf16_f32 v6, v6, v7
	v_cvt_pk_bf16_f32 v7, v8, v9
	v_cvt_pk_bf16_f32 v8, v2, v3
	v_cvt_pk_bf16_f32 v9, v4, v5
	s_andn2_b64 vcc, exec, s[38:39]
	s_mov_b64 s[22:23], -1
	s_movk_i32 s64, 0x4000
	s_mov_b32 s33, 0x18000
	s_mov_b32 s35, 0xa000
	s_mov_b32 s34, 0x1c000
	global_store_dwordx4 v146, v[6:9], s[0:1] offset:2048
	s_cbranch_vccnz .LBB0_1146
	s_andn2_b64 vcc, exec, s[16:17]
	s_cbranch_vccnz .LBB0_1145
	s_barrier
	s_branch .LBB0_1145
